# stack + MoBA phase: waves 4-7 take causal groups 7..4 so each SIMD pair owns equal own-block work
# baseline (speedup 1.0000x reference)
.LBB0_299:
	s_or_b64 exec, exec, s[0:1]
	s_add_u32 s28, s20, 0x13100000
	s_addc_u32 s29, s21, 0
	s_sub_i32 s0, 11, s89
	s_cmp_gt_u32 s89, 3
	s_cselect_b32 s89, s0, s89
	s_lshl_b32 s88, s89, 5
	v_readlane_b32 s0, v251, 36
	s_cmpk_gt_i32 s0, 0xff
	s_mul_i32 s0, s89, 0x1200
	s_waitcnt lgkmcnt(0)
	s_barrier
	v_writelane_b32 v250, s0, 4
	s_cbranch_scc1 .LBB0_409
	v_readlane_b32 s0, v251, 20
	s_and_b32 s0, s0, 0x7f8
	s_add_i32 s8, s89, s0
	s_mov_b32 s9, 0
	s_lshl_b64 s[0:1], s[8:9], 12
	s_add_u32 s0, s20, s0
	s_addc_u32 s1, s21, s1
	s_add_u32 s0, s0, 0x19100000
	v_lshlrev_b32_e32 v0, 3, v170
	s_mul_i32 s8, s89, 0x1200
	s_addc_u32 s1, s1, 0
	v_mov_b32_e32 v163, 0
	v_and_b32_e32 v0, 0xf8, v0
	s_add_i32 s8, s8, 0
	v_lshlrev_b32_e32 v2, 1, v0
	v_mov_b32_e32 v3, v163
	s_add_i32 s8, s8, 0x12000
	v_and_b32_e32 v171, 31, v168
	v_lshl_add_u64 v[166:167], s[96:97], 0, v[2:3]
	s_movk_i32 s10, 0x50
	v_mov_b32_e32 v2, s8
	v_ashrrev_i32_e32 v3, 1, v168
	v_mad_u32_u24 v12, v171, s10, v2
	v_mul_lo_u32 v2, v3, s10
	v_add_u32_e32 v13, s8, v2
	v_lshlrev_b32_e32 v2, 5, v168
	v_and_b32_e32 v219, 63, v3
	v_ashrrev_i32_e32 v3, 31, v2
	v_ashrrev_i32_e32 v169, 31, v168
	v_and_b32_e32 v172, 32, v2
	v_lshl_add_u64 v[174:175], s[0:1], 0, v[2:3]
	v_lshl_add_u64 v[2:3], v[168:169], 2, s[0:1]
	s_mov_b64 s[0:1], 0x800
	v_lshl_add_u64 v[176:177], v[2:3], 0, s[0:1]
	v_cmp_lt_i32_e64 s[0:1], 0, v170
	v_lshlrev_b32_e32 v4, 4, v170
	v_and_b32_e32 v2, 0x1f0, v4
	v_writelane_b32 v251, s0, 50
	v_add_u32_e32 v14, 0, v2
	v_ashrrev_i32_e32 v2, 5, v170
	v_writelane_b32 v251, s1, 51
	v_cmp_lt_i32_e64 s[0:1], 1, v170
	v_ashrrev_i32_e32 v3, 31, v2
	v_lshlrev_b64 v[178:179], 14, v[2:3]
	v_writelane_b32 v251, s0, 52
	v_add_u32_e32 v3, 0x200, v170
	v_and_b32_e32 v162, 0x70, v4
	v_writelane_b32 v251, s1, 53
	v_cmp_lt_i32_e64 s[0:1], 2, v170
	v_ashrrev_i32_e32 v220, 3, v3
	v_ashrrev_i32_e32 v4, 5, v3
	v_writelane_b32 v251, s0, 54
	v_add_u32_e32 v3, 0x400, v170
	v_ashrrev_i32_e32 v221, 3, v3
	v_writelane_b32 v251, s1, 55
	v_cmp_lt_i32_e64 s[0:1], 3, v170
	v_ashrrev_i32_e32 v6, 5, v3
	v_add_u32_e32 v3, 0x600, v170
	v_writelane_b32 v251, s0, 56
	v_ashrrev_i32_e32 v8, 5, v3
	v_ashrrev_i32_e32 v1, 5, v168
	v_writelane_b32 v251, s1, 57
	v_cmp_lt_i32_e64 s[0:1], 4, v170
	s_add_i32 s27, s89, 8
	s_movk_i32 s2, 0x90
	v_writelane_b32 v251, s0, 58
	s_movk_i32 s3, 0x210
	v_ashrrev_i32_e32 v169, 3, v170
	v_writelane_b32 v251, s1, 59
	v_cmp_lt_i32_e64 s[0:1], 5, v170
	v_ashrrev_i32_e32 v5, 31, v4
	v_ashrrev_i32_e32 v7, 31, v6
	v_writelane_b32 v251, s0, 60
	v_ashrrev_i32_e32 v222, 3, v3
	v_ashrrev_i32_e32 v9, 31, v8
	v_writelane_b32 v251, s1, 61
	v_cmp_lt_i32_e64 s[0:1], 6, v170
	s_add_i32 s26, 0, 0x23e00
	v_lshlrev_b32_e32 v160, 3, v1
	v_writelane_b32 v251, s0, 62
	v_lshl_or_b32 v200, s27, 5, v171
	v_lshl_add_u32 v10, v1, 4, 0
	v_writelane_b32 v251, s1, 63
	v_cmp_lt_i32_e64 s[0:1], 7, v170
	v_lshlrev_b32_e32 v203, 2, v1
	v_mul_u32_u24_e32 v1, 0x90, v171
	v_writelane_b32 v250, s0, 0
	v_mul_u32_u24_e32 v11, 0x210, v171
	v_add_u32_e32 v15, 0, v162
	v_writelane_b32 v250, s1, 1
	v_cmp_lt_i32_e64 s[0:1], 8, v170
	v_lshlrev_b64 v[180:181], 14, v[4:5]
	v_lshlrev_b64 v[182:183], 14, v[6:7]
	v_writelane_b32 v251, s0, 20
	v_lshlrev_b64 v[184:185], 14, v[8:9]
	v_mul_lo_u32 v3, v169, s2
	v_writelane_b32 v251, s1, 21
	v_cmp_lt_i32_e64 s[0:1], 9, v170
	v_mul_lo_u32 v2, v2, s3
	v_mul_lo_u32 v5, v220, s2
	v_writelane_b32 v250, s0, 2
	v_mul_lo_u32 v4, v4, s3
	v_mul_lo_u32 v7, v221, s2
	v_writelane_b32 v250, s1, 3
	v_cmp_lt_i32_e64 s[0:1], 10, v170
	v_mul_lo_u32 v6, v6, s3
	v_mul_lo_u32 v9, v222, s2
	v_writelane_b32 v250, s0, 5
	v_mul_lo_u32 v8, v8, s3
	v_lshlrev_b32_e32 v186, 1, v0
	v_writelane_b32 v250, s1, 6
	v_cmp_lt_i32_e64 s[0:1], 11, v170
	v_mbcnt_lo_u32_b32 v0, -1, 0
	v_cmp_gt_i32_e64 s[74:75], 32, v170
	v_writelane_b32 v250, s0, 7
	v_lshl_add_u32 v198, v170, 2, s26
	v_cmp_eq_u32_e64 s[6:7], 0, v170
	v_writelane_b32 v250, s1, 8
	v_cmp_lt_i32_e64 s[0:1], 12, v170
	v_ashrrev_i32_e32 v161, 31, v160
	v_lshl_add_u64 v[164:165], s[58:59], 0, v[162:163]
	v_writelane_b32 v250, s0, 9
	v_or_b32_e32 v199, s88, v171
	v_add_u32_e32 v201, 0xffffff00, v200
	v_writelane_b32 v250, s1, 10
	v_cmp_lt_i32_e64 s[0:1], 13, v170
	v_or_b32_e32 v202, 0xffffffe0, v168
	v_or_b32_e32 v204, 2, v203
	v_writelane_b32 v250, s0, 11
	v_or_b32_e32 v205, 3, v203
	v_add_u32_e32 v206, 8, v203
	v_writelane_b32 v250, s1, 12
	v_cmp_lt_i32_e64 s[0:1], 14, v170
	v_add_u32_e32 v207, 9, v203
	v_add_u32_e32 v208, 10, v203
	v_writelane_b32 v250, s0, 13
	v_add_u32_e32 v209, 11, v203
	v_add_u32_e32 v210, 16, v203
	v_writelane_b32 v250, s1, 14
	v_cmp_lt_i32_e64 s[0:1], 15, v170
	v_add_u32_e32 v211, 17, v203
	v_add_u32_e32 v212, 18, v203
	v_writelane_b32 v250, s0, 15
	v_add_u32_e32 v213, 19, v203
	v_add_u32_e32 v214, 24, v203
	v_writelane_b32 v250, s1, 16
	v_cmp_lt_i32_e64 s[0:1], 16, v170
	v_add_u32_e32 v216, 25, v203
	v_add_u32_e32 v217, 26, v203
	v_writelane_b32 v250, s0, 17
	v_add_u32_e32 v218, 27, v203
	v_mov_b32_e32 v173, v163
	v_writelane_b32 v250, s1, 18
	v_cmp_lt_i32_e64 s[0:1], 17, v170
	s_add_i32 s39, 0, 0x23e80
	s_add_i32 s40, 0, 0x23f00
	v_writelane_b32 v250, s0, 19
	s_add_i32 s43, 0, 0x23ebc
	s_add_i32 s44, 0, 0x23ec0
	v_writelane_b32 v250, s1, 20
	s_add_i32 s0, 0, 0x23e10
	v_writelane_b32 v250, s0, 21
	s_add_i32 s0, 0, 0x23e20
	v_writelane_b32 v250, s0, 23
	s_add_i32 s0, 0, 0x23e30
	v_writelane_b32 v250, s0, 25
	s_add_i32 s0, 0, 0x23e40
	v_writelane_b32 v250, s0, 27
	s_add_i32 s0, 0, 0x23e50
	v_writelane_b32 v250, s0, 29
	s_add_i32 s0, 0, 0x23e60
	v_writelane_b32 v250, s0, 31
	s_add_i32 s0, 0, 0x23e70
	v_writelane_b32 v250, s0, 33
	s_add_i32 s0, 0, 0x23e84
	v_writelane_b32 v250, s0, 35
	s_add_i32 s0, 0, 0x23e88
	v_writelane_b32 v250, s0, 36
	s_add_i32 s0, 0, 0x23e8c
	v_writelane_b32 v250, s0, 37
	s_add_i32 s0, 0, 0x23e90
	v_writelane_b32 v250, s0, 38
	s_add_i32 s0, 0, 0x23e94
	v_writelane_b32 v250, s0, 39
	s_add_i32 s0, 0, 0x23e98
	v_writelane_b32 v250, s0, 40
	s_add_i32 s0, 0, 0x23e9c
	v_writelane_b32 v250, s0, 41
	s_add_i32 s0, 0, 0x23ea0
	v_writelane_b32 v250, s0, 42
	s_add_i32 s0, 0, 0x23ea4
	v_writelane_b32 v250, s0, 43
	s_add_i32 s0, 0, 0x23ea8
	v_writelane_b32 v250, s0, 44
	s_add_i32 s0, 0, 0x23eac
	v_writelane_b32 v250, s0, 45
	s_add_i32 s0, 0, 0x23eb0
	v_writelane_b32 v250, s0, 46
	s_add_i32 s0, 0, 0x23eb4
	v_writelane_b32 v250, s0, 47
	s_add_i32 s0, 0, 0x23eb8
	v_writelane_b32 v250, s0, 48
	s_add_i32 s0, 0, 0x23efc
	v_writelane_b32 v250, s0, 49
	v_cmp_lt_i32_e64 s[0:1], 18, v170
	s_add_i32 s45, 0, 0x23ec4
	s_add_i32 s30, 0, 0x23ec8
	v_writelane_b32 v250, s0, 50
	s_add_i32 s31, 0, 0x23ecc
	s_add_i32 s34, 0, 0x23ed0
	v_writelane_b32 v250, s1, 51
	v_cmp_lt_i32_e64 s[0:1], 19, v170
	s_add_i32 s46, 0, 0x23ed4
	s_add_i32 s47, 0, 0x23ed8
	v_writelane_b32 v250, s0, 52
	s_add_i32 s35, 0, 0x23edc
	s_add_i32 s48, 0, 0x23ee0
	v_writelane_b32 v250, s1, 53
	v_cmp_lt_i32_e64 s[0:1], 20, v170
	s_add_i32 s49, 0, 0x23ee4
	s_add_i32 s36, 0, 0x23ee8
	v_writelane_b32 v250, s0, 54
	s_add_i32 s50, 0, 0x23eec
	s_add_i32 s51, 0, 0x23ef0
	v_writelane_b32 v250, s1, 55
	v_cmp_lt_i32_e64 s[0:1], 21, v170
	s_add_i32 s37, 0, 0x23ef4
	s_add_i32 s52, 0, 0x23ef8
	v_writelane_b32 v250, s0, 56
	s_add_i32 s53, 0, 0x23f80
	v_add_u32_e32 v223, v15, v3
	v_writelane_b32 v250, s1, 57
	v_cmp_lt_i32_e64 s[0:1], 22, v170
	v_add_u32_e32 v224, v14, v2
	v_add_u32_e32 v225, v15, v5
	v_writelane_b32 v250, s0, 58
	v_add_u32_e32 v226, v14, v4
	v_add_u32_e32 v227, v15, v7
	v_writelane_b32 v250, s1, 59
	v_cmp_lt_i32_e64 s[0:1], 23, v170
	v_add_u32_e32 v228, v14, v6
	v_add_u32_e32 v229, v15, v9
	v_writelane_b32 v250, s0, 60
	v_add_u32_e32 v230, v14, v8
	s_mov_b32 s38, 0xff800000
	v_writelane_b32 v250, s1, 61
	v_cmp_lt_i32_e64 s[0:1], 24, v170
	v_add_u32_e32 v231, v12, v203
	v_mbcnt_hi_u32_b32 v232, -1, v0
	v_add_u32_e32 v233, v10, v1
	v_add_u32_e32 v234, v10, v11
	v_mov_b32_e32 v235, 0xff800000
	v_mov_b32_e32 v236, 0x8000
	v_add_u32_e32 v237, v13, v172
	v_readlane_b32 s33, v251, 36
	v_writelane_b32 v250, s0, 62
	v_cmp_lt_i32_e64 s[60:61], 25, v170
	v_cmp_lt_i32_e64 s[62:63], 26, v170
	v_cmp_lt_i32_e64 s[64:65], 27, v170
	v_cmp_lt_i32_e64 s[66:67], 28, v170
	v_cmp_lt_i32_e64 s[68:69], 29, v170
	v_cmp_eq_u32_e64 s[70:71], 31, v170
	v_writelane_b32 v250, s1, 63
	s_branch .LBB0_303

.LBB0_409:
	s_waitcnt lgkmcnt(0)
	s_barrier
	s_waitcnt vmcnt(0)
	s_barrier
	s_sub_i32 s0, 11, s89
	s_cmp_gt_u32 s89, 3
	s_cselect_b32 s89, s0, s89
	s_lshl_b32 s88, s89, 5
	s_mul_i32 s0, s89, 0x1200
	s_nop 0
	v_writelane_b32 v250, s0, 4
	s_mov_b64 s[0:1], exec
	v_readlane_b32 s2, v251, 17
	v_readlane_b32 s3, v251, 18
	v_readlane_b32 s92, v251, 34
	s_and_b64 s[2:3], s[0:1], s[2:3]
	v_readlane_b32 s93, v251, 35
	v_readlane_b32 s96, v251, 32
	v_readlane_b32 s68, v251, 24
	v_readlane_b32 s70, v251, 26
	s_xor_b64 s[0:1], s[2:3], s[0:1]
	v_readlane_b32 s97, v251, 33
	v_readlane_b32 s93, v251, 49
	v_readlane_b32 s84, v251, 36
	v_readlane_b32 s85, v251, 40
	v_readlane_b32 s69, v251, 25
	v_readlane_b32 s71, v251, 27
	s_mov_b64 exec, s[2:3]
	s_cbranch_execz .LBB0_462
	s_add_i32 s2, 0, 0x23d00
	v_mov_b32_e32 v0, s2
	s_waitcnt vmcnt(0) expcnt(0) lgkmcnt(0)
	ds_read_b32 v2, v0
	s_add_i32 s2, 0, 0x23d04
	v_mov_b32_e32 v0, s2
	ds_read_b32 v0, v0
	s_waitcnt lgkmcnt(1)
	v_cmp_ne_u32_e32 vcc, 0, v2
	s_cbranch_vccnz .LBB0_425
	v_readlane_b32 s2, v251, 0
	s_mul_i32 s33, s23, s2
	s_add_u32 s2, s20, 0x4200
	s_addc_u32 s3, s21, 0
	s_add_u32 s6, s20, 0x4400
	s_addc_u32 s7, s21, 0
	s_add_u32 s8, s20, 0x4500
	s_addc_u32 s9, s21, 0
	s_add_u32 s10, s20, 0x4600
	s_addc_u32 s11, s21, 0
	s_add_u32 s26, s20, 0x4700
	s_addc_u32 s27, s21, 0
	s_add_u32 s30, s20, 0x4800
	s_addc_u32 s31, s21, 0
	s_add_u32 s34, s20, 0x4900
	s_addc_u32 s35, s21, 0
	s_add_u32 s36, s20, 0x4a00
	s_addc_u32 s37, s21, 0
	s_add_u32 s38, s20, 0x4b00
	s_addc_u32 s39, s21, 0
	s_add_u32 s40, s20, 0x4c00
	s_addc_u32 s41, s21, 0
	s_add_u32 s42, s20, 0x4d00
	s_addc_u32 s43, s21, 0
	s_add_u32 s44, s20, 0x4e00
	s_addc_u32 s45, s21, 0
	s_add_u32 s46, s20, 0x4f00
	s_addc_u32 s47, s21, 0
	s_add_u32 s48, s20, 0x5000
	s_addc_u32 s49, s21, 0
	s_add_u32 s50, s20, 0x5100
	s_addc_u32 s51, s21, 0
	s_add_u32 s52, s20, 0x5200
	s_addc_u32 s53, s21, 0
	s_add_u32 s54, s20, 0x5300
	s_mul_i32 s33, s33, s22
	s_addc_u32 s55, s21, 0
	s_mov_b32 s62, 1
	v_mov_b32_e32 v16, 0
	s_branch .LBB0_413
